# in-projection gate epilogue: 4x4 dword transpose across the four fq lane rows (permlane16/32 swap), one 16-byte store per lane instead of four 4-byte stores; bit-identical
# speedup vs baseline: 1.0699x; 1.0083x over previous
;     __device__ __forceinline__ void operator()(const f32x4 (&acc)[2][2][4][2], const pg8::Unit& u, int wr, int wc, int fr_, int fq_) const {
;     ...
;         const int pm = u.pm, pn = u.pn;
;         const bool lat = pm < 64;
;         const int b = lat ? (pm >> 5) : (pm - 64);
;         const int kvb = lat ? ((pm & 31) << 8) : SEQ;
;         const int rl0 = wr * 64 + fr;
;         if (pn < 9) {
;     ...
;             const int g0 = (pn - 12) * 256 + 32 * wc + 4 * fq;
; #pragma unroll
;             for (int ai = 0; ai < 2; ++ai)
; #pragma unroll
;                 for (int m = 0; m < 4; ++m) {
;                     unsigned char* rowp = (unsigned char*)G + ((size_t)pm * 256 + ai * 128 + rl0 + m * 16) * 3072 + g0;
; #pragma unroll
;                     for (int bj = 0; bj < 2; ++bj)
; #pragma unroll
;                         for (int n = 0; n < 2; ++n) {
;                             const f32x4 x = acc[ai][bj][m][n]; f32x4 y;
; #pragma unroll
;                             for (int j = 0; j < 4; ++j) y[j] = __builtin_amdgcn_rcpf(1.f + __expf(-x[j]));
;                             const unsigned w = (unsigned)(y[0] * 255.f + 0.5f) | ((unsigned)(y[1] * 255.f + 0.5f) << 8) | ((unsigned)(y[2] * 255.f + 0.5f) << 16) | ((unsigned)(y[3] * 255.f + 0.5f) << 24);
;                             *(unsigned*)(rowp + 128 * bj + 16 * n) = w;
;                         }
.LBB0_232:
	s_lshl_b32 s6, s8, 8
	s_ashr_i32 s1, s8, 5
	s_sub_i32 s3, s8, 64
	s_and_b32 s23, s6, 0x1f00
	s_cmp_lt_i32 s8, 64
	s_cselect_b64 s[34:35], -1, 0
	v_mov_b32_e32 v150, v146
	v_mov_b32_e32 v0, v147
	s_and_b64 s[6:7], s[34:35], exec
	s_cselect_b32 s25, s1, s3
	s_cselect_b32 s1, s23, 0x2000
	v_add_u32_e32 v138, s55, v150
	s_cmp_gt_i32 s2, 8
	s_mov_b64 s[6:7], -1
	s_cbranch_scc0 .LBB0_239
	s_cmp_gt_u32 s2, 11
	s_cbranch_scc0 .LBB0_235
	s_lshl_b32 s3, s2, 8
	s_add_i32 s3, s59, s3
	v_lshl_add_u32 v140, v0, 2, s3
	s_ashr_i32 s9, s8, 31
	s_lshl_b64 s[6:7], s[8:9], 8
	v_ashrrev_i32_e32 v139, 31, v138
	v_ashrrev_i32_e32 v141, 31, v140
	v_lshl_add_u64 v[142:143], s[6:7], 0, v[138:139]
	v_lshl_add_u64 v[140:141], s[20:21], 0, v[140:141]
	v_mad_u64_u32 v[140:141], s[6:7], v142, s86, v[140:141]
	v_mul_f32_e32 v139, 0xbfb8aa3b, v126
	v_mul_f32_e32 v142, 0xbfb8aa3b, v127
	v_exp_f32_e32 v139, v139
	v_exp_f32_e32 v142, v142
	v_mad_i32_i24 v141, v143, s86, v141
	v_mul_f32_e32 v143, 0xbfb8aa3b, v128
	v_add_f32_e32 v139, 1.0, v139
	v_add_f32_e32 v142, 1.0, v142
	v_mul_f32_e32 v144, 0xbfb8aa3b, v129
	v_rcp_f32_e32 v139, v139
	v_rcp_f32_e32 v142, v142
	v_exp_f32_e32 v143, v143
	v_exp_f32_e32 v144, v144
	v_fma_f32 v139, v139, s87, 0.5
	v_fma_f32 v142, v142, s87, 0.5
	v_add_f32_e32 v143, 1.0, v143
	v_add_f32_e32 v144, 1.0, v144
	v_rcp_f32_e32 v143, v143
	v_rcp_f32_e32 v144, v144
	v_cvt_u32_f32_e32 v139, v139
	v_cvt_u32_f32_e32 v142, v142
	s_mov_b32 s3, 0xc000
	v_mul_f32_e32 v145, 0xbfb8aa3b, v104
	v_mul_f32_e32 v151, 0xbfb8aa3b, v105
	v_lshl_or_b32 v139, v142, 8, v139
	v_fma_f32 v142, v143, s87, 0.5
	v_fma_f32 v143, v144, s87, 0.5
	v_cvt_u32_f32_sdwa v142, v142 dst_sel:WORD_1 dst_unused:UNUSED_PAD src0_sel:DWORD
	v_cvt_u32_f32_sdwa v143, v143 dst_sel:BYTE_3 dst_unused:UNUSED_PAD src0_sel:DWORD
	v_mul_f32_e32 v144, 0xbfb8aa3b, v121
	v_exp_f32_e32 v144, v144
	v_exp_f32_e32 v145, v145
	v_lshrrev_b32_e32 v172, 4, v185
	v_and_b32_e32 v173, 1, v172
	v_bfe_u32 v174, v172, 1, 1
	v_and_b32_e32 v172, 3, v172
	v_lshlrev_b32_e32 v173, 4, v173
	v_lshl_add_u32 v173, v174, 7, v173
	v_lshlrev_b32_e32 v172, 2, v172
	v_sub_u32_e32 v172, v173, v172
	v_mov_b32_e32 v173, 0
	v_or3_b32 v166, v139, v142, v143
	v_mul_f32_e32 v139, 0xbfb8aa3b, v118
	v_mul_f32_e32 v142, 0xbfb8aa3b, v119
	v_exp_f32_e32 v139, v139
	v_exp_f32_e32 v142, v142
	v_mul_f32_e32 v143, 0xbfb8aa3b, v120
	v_exp_f32_e32 v143, v143
	v_add_f32_e32 v139, 1.0, v139
	v_add_f32_e32 v142, 1.0, v142
	v_rcp_f32_e32 v139, v139
	v_rcp_f32_e32 v142, v142
	v_add_f32_e32 v143, 1.0, v143
	v_add_f32_e32 v144, 1.0, v144
	v_fma_f32 v139, v139, s87, 0.5
	v_fma_f32 v142, v142, s87, 0.5
	v_rcp_f32_e32 v143, v143
	v_rcp_f32_e32 v144, v144
	v_cvt_u32_f32_e32 v139, v139
	v_cvt_u32_f32_e32 v142, v142
	v_exp_f32_e32 v151, v151
	v_add_f32_e32 v145, 1.0, v145
	v_rcp_f32_e32 v145, v145
	v_lshl_or_b32 v139, v142, 8, v139
	v_fma_f32 v142, v143, s87, 0.5
	v_fma_f32 v143, v144, s87, 0.5
	v_cvt_u32_f32_sdwa v142, v142 dst_sel:WORD_1 dst_unused:UNUSED_PAD src0_sel:DWORD
	v_cvt_u32_f32_sdwa v143, v143 dst_sel:BYTE_3 dst_unused:UNUSED_PAD src0_sel:DWORD
	v_mul_f32_e32 v144, 0xbfb8aa3b, v125
	v_exp_f32_e32 v144, v144
	v_add_f32_e32 v151, 1.0, v151
	v_or3_b32 v167, v139, v142, v143
	v_mul_f32_e32 v139, 0xbfb8aa3b, v122
	v_mul_f32_e32 v142, 0xbfb8aa3b, v123
	v_exp_f32_e32 v139, v139
	v_exp_f32_e32 v142, v142
	v_mul_f32_e32 v143, 0xbfb8aa3b, v124
	v_exp_f32_e32 v143, v143
	v_add_f32_e32 v139, 1.0, v139
	v_add_f32_e32 v142, 1.0, v142
	v_rcp_f32_e32 v139, v139
	v_rcp_f32_e32 v142, v142
	v_add_f32_e32 v143, 1.0, v143
	v_add_f32_e32 v144, 1.0, v144
	v_fma_f32 v139, v139, s87, 0.5
	v_fma_f32 v142, v142, s87, 0.5
	v_rcp_f32_e32 v143, v143
	v_rcp_f32_e32 v144, v144
	v_cvt_u32_f32_e32 v139, v139
	v_cvt_u32_f32_e32 v142, v142
	v_rcp_f32_e32 v151, v151
	s_mov_b64 s[6:7], 0
	v_lshl_or_b32 v139, v142, 8, v139
	v_fma_f32 v142, v143, s87, 0.5
	v_fma_f32 v143, v144, s87, 0.5
	v_cvt_u32_f32_sdwa v142, v142 dst_sel:WORD_1 dst_unused:UNUSED_PAD src0_sel:DWORD
	v_cvt_u32_f32_sdwa v143, v143 dst_sel:BYTE_3 dst_unused:UNUSED_PAD src0_sel:DWORD
	v_mul_f32_e32 v144, 0xbfb8aa3b, v117
	v_exp_f32_e32 v144, v144
	v_or3_b32 v168, v139, v142, v143
	v_mul_f32_e32 v139, 0xbfb8aa3b, v114
	v_mul_f32_e32 v142, 0xbfb8aa3b, v115
	v_exp_f32_e32 v139, v139
	v_exp_f32_e32 v142, v142
	v_mul_f32_e32 v143, 0xbfb8aa3b, v116
	v_exp_f32_e32 v143, v143
	v_add_f32_e32 v139, 1.0, v139
	v_add_f32_e32 v142, 1.0, v142
	v_rcp_f32_e32 v139, v139
	v_rcp_f32_e32 v142, v142
	v_add_f32_e32 v143, 1.0, v143
	v_add_f32_e32 v144, 1.0, v144
	v_fma_f32 v139, v139, s87, 0.5
	v_fma_f32 v142, v142, s87, 0.5
	v_rcp_f32_e32 v143, v143
	v_rcp_f32_e32 v144, v144
	v_cvt_u32_f32_e32 v139, v139
	v_cvt_u32_f32_e32 v142, v142
	v_lshl_or_b32 v139, v142, 8, v139
	v_fma_f32 v142, v143, s87, 0.5
	v_fma_f32 v143, v144, s87, 0.5
	v_cvt_u32_f32_sdwa v142, v142 dst_sel:WORD_1 dst_unused:UNUSED_PAD src0_sel:DWORD
	v_cvt_u32_f32_sdwa v143, v143 dst_sel:BYTE_3 dst_unused:UNUSED_PAD src0_sel:DWORD
	v_mul_f32_e32 v144, 0xbfb8aa3b, v113
	v_exp_f32_e32 v144, v144
	v_or3_b32 v169, v139, v142, v143
	s_nop 1
	v_permlane16_swap_b32_e32 v166, v167
	v_permlane16_swap_b32_e32 v168, v169
	s_nop 1
	v_permlane32_swap_b32_e32 v166, v168
	v_permlane32_swap_b32_e32 v167, v169
	v_lshl_add_u64 v[170:171], v[140:141], 0, v[172:173]
	global_store_dwordx4 v[170:171], v[166:169], off
	v_mul_f32_e32 v139, 0xbfb8aa3b, v110
	v_mul_f32_e32 v142, 0xbfb8aa3b, v111
	v_exp_f32_e32 v139, v139
	v_exp_f32_e32 v142, v142
	v_mul_f32_e32 v143, 0xbfb8aa3b, v112
	v_exp_f32_e32 v143, v143
	v_add_f32_e32 v139, 1.0, v139
	v_add_f32_e32 v142, 1.0, v142
	v_rcp_f32_e32 v139, v139
;     __device__ __forceinline__ void operator()(const f32x4 (&acc)[2][2][4][2], const pg8::Unit& u, int wr, int wc, int fr_, int fq_) const {
;     ...
; #pragma unroll
;             for (int ai = 0; ai < 2; ++ai)
; #pragma unroll
;                 for (int m = 0; m < 4; ++m) {
;                     unsigned char* rowp = (unsigned char*)G + ((size_t)pm * 256 + ai * 128 + rl0 + m * 16) * 3072 + g0;
; #pragma unroll
;                     for (int bj = 0; bj < 2; ++bj)
; #pragma unroll
;                         for (int n = 0; n < 2; ++n) {
;                             const f32x4 x = acc[ai][bj][m][n]; f32x4 y;
; #pragma unroll
;                             for (int j = 0; j < 4; ++j) y[j] = __builtin_amdgcn_rcpf(1.f + __expf(-x[j]));
;                             const unsigned w = (unsigned)(y[0] * 255.f + 0.5f) | ((unsigned)(y[1] * 255.f + 0.5f) << 8) | ((unsigned)(y[2] * 255.f + 0.5f) << 16) | ((unsigned)(y[3] * 255.f + 0.5f) << 24);
;                             *(unsigned*)(rowp + 128 * bj + 16 * n) = w;
	v_rcp_f32_e32 v142, v142
	v_add_f32_e32 v143, 1.0, v143
	v_add_f32_e32 v144, 1.0, v144
	v_fma_f32 v139, v139, s87, 0.5
	v_fma_f32 v142, v142, s87, 0.5
	v_rcp_f32_e32 v143, v143
	v_rcp_f32_e32 v144, v144
	v_cvt_u32_f32_e32 v139, v139
	v_cvt_u32_f32_e32 v142, v142
	v_lshl_or_b32 v139, v142, 8, v139
	v_fma_f32 v142, v143, s87, 0.5
	v_fma_f32 v143, v144, s87, 0.5
	v_cvt_u32_f32_sdwa v142, v142 dst_sel:WORD_1 dst_unused:UNUSED_PAD src0_sel:DWORD
	v_cvt_u32_f32_sdwa v143, v143 dst_sel:BYTE_3 dst_unused:UNUSED_PAD src0_sel:DWORD
	v_mul_f32_e32 v144, 0xbfb8aa3b, v103
	v_exp_f32_e32 v144, v144
	v_or3_b32 v166, v139, v142, v143
	v_add_co_u32_e32 v142, vcc, s3, v140
	v_add_f32_e32 v144, 1.0, v144
	s_nop 0
	v_addc_co_u32_e32 v143, vcc, 0, v141, vcc
	v_mul_f32_e32 v139, 0xbfb8aa3b, v102
	v_exp_f32_e32 v139, v139
	v_rcp_f32_e32 v144, v144
	s_mov_b32 s3, 0x18000
	v_add_f32_e32 v139, 1.0, v139
	v_rcp_f32_e32 v139, v139
	v_fma_f32 v144, v144, s87, 0.5
	v_cvt_u32_f32_e32 v144, v144
	v_fma_f32 v139, v139, s87, 0.5
	v_cvt_u32_f32_e32 v139, v139
	v_lshl_or_b32 v139, v144, 8, v139
	v_fma_f32 v144, v145, s87, 0.5
	v_fma_f32 v145, v151, s87, 0.5
	v_cvt_u32_f32_sdwa v144, v144 dst_sel:WORD_1 dst_unused:UNUSED_PAD src0_sel:DWORD
	v_cvt_u32_f32_sdwa v145, v145 dst_sel:BYTE_3 dst_unused:UNUSED_PAD src0_sel:DWORD
	v_mul_f32_e32 v151, 0xbfb8aa3b, v109
	v_exp_f32_e32 v151, v151
	v_or3_b32 v167, v139, v144, v145
	v_mul_f32_e32 v139, 0xbfb8aa3b, v106
	v_mul_f32_e32 v144, 0xbfb8aa3b, v107
	v_exp_f32_e32 v139, v139
	v_exp_f32_e32 v144, v144
	v_mul_f32_e32 v145, 0xbfb8aa3b, v108
	v_exp_f32_e32 v145, v145
	v_add_f32_e32 v139, 1.0, v139
	v_add_f32_e32 v144, 1.0, v144
	v_rcp_f32_e32 v139, v139
	v_rcp_f32_e32 v144, v144
	v_add_f32_e32 v145, 1.0, v145
	v_add_f32_e32 v151, 1.0, v151
	v_fma_f32 v139, v139, s87, 0.5
	v_fma_f32 v144, v144, s87, 0.5
	v_rcp_f32_e32 v145, v145
	v_rcp_f32_e32 v151, v151
	v_cvt_u32_f32_e32 v139, v139
	v_cvt_u32_f32_e32 v144, v144
	v_lshl_or_b32 v139, v144, 8, v139
	v_fma_f32 v144, v145, s87, 0.5
	v_fma_f32 v145, v151, s87, 0.5
	v_cvt_u32_f32_sdwa v144, v144 dst_sel:WORD_1 dst_unused:UNUSED_PAD src0_sel:DWORD
	v_cvt_u32_f32_sdwa v145, v145 dst_sel:BYTE_3 dst_unused:UNUSED_PAD src0_sel:DWORD
	v_mul_f32_e32 v151, 0xbfb8aa3b, v101
	v_exp_f32_e32 v151, v151
	v_or3_b32 v168, v139, v144, v145
	v_mul_f32_e32 v139, 0xbfb8aa3b, v98
	v_mul_f32_e32 v144, 0xbfb8aa3b, v99
	v_exp_f32_e32 v139, v139
	v_exp_f32_e32 v144, v144
	v_mul_f32_e32 v145, 0xbfb8aa3b, v100
	v_exp_f32_e32 v145, v145
	v_add_f32_e32 v139, 1.0, v139
	v_add_f32_e32 v144, 1.0, v144
	v_rcp_f32_e32 v139, v139
	v_rcp_f32_e32 v144, v144
	v_add_f32_e32 v145, 1.0, v145
	v_add_f32_e32 v151, 1.0, v151
	v_fma_f32 v139, v139, s87, 0.5
	v_fma_f32 v144, v144, s87, 0.5
	v_rcp_f32_e32 v145, v145
	v_rcp_f32_e32 v151, v151
	v_cvt_u32_f32_e32 v139, v139
	v_cvt_u32_f32_e32 v144, v144
	v_lshl_or_b32 v139, v144, 8, v139
	v_fma_f32 v144, v145, s87, 0.5
	v_fma_f32 v145, v151, s87, 0.5
	v_cvt_u32_f32_sdwa v144, v144 dst_sel:WORD_1 dst_unused:UNUSED_PAD src0_sel:DWORD
	v_cvt_u32_f32_sdwa v145, v145 dst_sel:BYTE_3 dst_unused:UNUSED_PAD src0_sel:DWORD
	v_mul_f32_e32 v151, 0xbfb8aa3b, v89
	v_exp_f32_e32 v151, v151
	v_or3_b32 v169, v139, v144, v145
	s_nop 1
	v_permlane16_swap_b32_e32 v166, v167
	v_permlane16_swap_b32_e32 v168, v169
	s_nop 1
	v_permlane32_swap_b32_e32 v166, v168
	v_permlane32_swap_b32_e32 v167, v169
	v_lshl_add_u64 v[170:171], v[142:143], 0, v[172:173]
	global_store_dwordx4 v[170:171], v[166:169], off
	v_mul_f32_e32 v139, 0xbfb8aa3b, v94
	v_mul_f32_e32 v142, 0xbfb8aa3b, v95
	v_exp_f32_e32 v139, v139
	v_exp_f32_e32 v142, v142
	v_mul_f32_e32 v143, 0xbfb8aa3b, v96
	v_mul_f32_e32 v144, 0xbfb8aa3b, v97
	v_add_f32_e32 v139, 1.0, v139
	v_add_f32_e32 v142, 1.0, v142
	v_rcp_f32_e32 v139, v139
	v_rcp_f32_e32 v142, v142
	v_exp_f32_e32 v143, v143
	v_exp_f32_e32 v144, v144
	v_fma_f32 v139, v139, s87, 0.5
	v_fma_f32 v142, v142, s87, 0.5
	v_add_f32_e32 v143, 1.0, v143
	v_add_f32_e32 v144, 1.0, v144
	v_rcp_f32_e32 v143, v143
	v_rcp_f32_e32 v144, v144
	v_cvt_u32_f32_e32 v139, v139
	v_cvt_u32_f32_e32 v142, v142
	v_mul_f32_e32 v145, 0xbfb8aa3b, v88
	v_exp_f32_e32 v145, v145
	v_add_f32_e32 v151, 1.0, v151
	v_lshl_or_b32 v139, v142, 8, v139
	v_fma_f32 v142, v143, s87, 0.5
	v_fma_f32 v143, v144, s87, 0.5
	v_cvt_u32_f32_sdwa v142, v142 dst_sel:WORD_1 dst_unused:UNUSED_PAD src0_sel:DWORD
	v_cvt_u32_f32_sdwa v143, v143 dst_sel:BYTE_3 dst_unused:UNUSED_PAD src0_sel:DWORD
	v_mul_f32_e32 v144, 0xbfb8aa3b, v87
	v_exp_f32_e32 v144, v144
	v_add_f32_e32 v145, 1.0, v145
	v_or3_b32 v166, v139, v142, v143
	v_add_co_u32_e32 v142, vcc, s3, v140
	v_add_f32_e32 v144, 1.0, v144
	s_nop 0
	v_addc_co_u32_e32 v143, vcc, 0, v141, vcc
	v_mul_f32_e32 v139, 0xbfb8aa3b, v86
	v_exp_f32_e32 v139, v139
	v_rcp_f32_e32 v144, v144
	v_rcp_f32_e32 v145, v145
	v_rcp_f32_e32 v151, v151
	v_add_f32_e32 v139, 1.0, v139
	v_rcp_f32_e32 v139, v139
	v_fma_f32 v144, v144, s87, 0.5
	v_cvt_u32_f32_e32 v144, v144
	s_mov_b32 s3, 0x24000
	v_fma_f32 v139, v139, s87, 0.5
	v_cvt_u32_f32_e32 v139, v139
	v_lshl_or_b32 v139, v144, 8, v139
	v_fma_f32 v144, v145, s87, 0.5
	v_fma_f32 v145, v151, s87, 0.5
	v_cvt_u32_f32_sdwa v144, v144 dst_sel:WORD_1 dst_unused:UNUSED_PAD src0_sel:DWORD
	v_cvt_u32_f32_sdwa v145, v145 dst_sel:BYTE_3 dst_unused:UNUSED_PAD src0_sel:DWORD
	v_mul_f32_e32 v151, 0xbfb8aa3b, v93
	v_exp_f32_e32 v151, v151
	v_or3_b32 v167, v139, v144, v145
	v_mul_f32_e32 v139, 0xbfb8aa3b, v90
	v_mul_f32_e32 v144, 0xbfb8aa3b, v91
	v_exp_f32_e32 v139, v139
	v_exp_f32_e32 v144, v144
	v_mul_f32_e32 v145, 0xbfb8aa3b, v92
	v_exp_f32_e32 v145, v145
	v_add_f32_e32 v139, 1.0, v139
;     __device__ __forceinline__ void operator()(const f32x4 (&acc)[2][2][4][2], const pg8::Unit& u, int wr, int wc, int fr_, int fq_) const {
;     ...
; #pragma unroll
;             for (int ai = 0; ai < 2; ++ai)
; #pragma unroll
;                 for (int m = 0; m < 4; ++m) {
;                     unsigned char* rowp = (unsigned char*)G + ((size_t)pm * 256 + ai * 128 + rl0 + m * 16) * 3072 + g0;
; #pragma unroll
;                     for (int bj = 0; bj < 2; ++bj)
; #pragma unroll
;                         for (int n = 0; n < 2; ++n) {
;                             const f32x4 x = acc[ai][bj][m][n]; f32x4 y;
; #pragma unroll
;                             for (int j = 0; j < 4; ++j) y[j] = __builtin_amdgcn_rcpf(1.f + __expf(-x[j]));
;                             const unsigned w = (unsigned)(y[0] * 255.f + 0.5f) | ((unsigned)(y[1] * 255.f + 0.5f) << 8) | ((unsigned)(y[2] * 255.f + 0.5f) << 16) | ((unsigned)(y[3] * 255.f + 0.5f) << 24);
;                             *(unsigned*)(rowp + 128 * bj + 16 * n) = w;
	v_add_f32_e32 v144, 1.0, v144
	v_rcp_f32_e32 v139, v139
	v_rcp_f32_e32 v144, v144
	v_add_f32_e32 v145, 1.0, v145
	v_add_f32_e32 v151, 1.0, v151
	v_fma_f32 v139, v139, s87, 0.5
	v_fma_f32 v144, v144, s87, 0.5
	v_rcp_f32_e32 v145, v145
	v_rcp_f32_e32 v151, v151
	v_cvt_u32_f32_e32 v139, v139
	v_cvt_u32_f32_e32 v144, v144
	v_lshl_or_b32 v139, v144, 8, v139
	v_fma_f32 v144, v145, s87, 0.5
	v_fma_f32 v145, v151, s87, 0.5
	v_cvt_u32_f32_sdwa v144, v144 dst_sel:WORD_1 dst_unused:UNUSED_PAD src0_sel:DWORD
	v_cvt_u32_f32_sdwa v145, v145 dst_sel:BYTE_3 dst_unused:UNUSED_PAD src0_sel:DWORD
	v_mul_f32_e32 v151, 0xbfb8aa3b, v85
	v_exp_f32_e32 v151, v151
	v_or3_b32 v168, v139, v144, v145
	v_mul_f32_e32 v139, 0xbfb8aa3b, v82
	v_mul_f32_e32 v144, 0xbfb8aa3b, v83
	v_exp_f32_e32 v139, v139
	v_exp_f32_e32 v144, v144
	v_mul_f32_e32 v145, 0xbfb8aa3b, v84
	v_exp_f32_e32 v145, v145
	v_add_f32_e32 v139, 1.0, v139
	v_add_f32_e32 v144, 1.0, v144
	v_rcp_f32_e32 v139, v139
	v_rcp_f32_e32 v144, v144
	v_add_f32_e32 v145, 1.0, v145
	v_add_f32_e32 v151, 1.0, v151
	v_fma_f32 v139, v139, s87, 0.5
	v_fma_f32 v144, v144, s87, 0.5
	v_rcp_f32_e32 v145, v145
	v_rcp_f32_e32 v151, v151
	v_cvt_u32_f32_e32 v139, v139
	v_cvt_u32_f32_e32 v144, v144
	v_lshl_or_b32 v139, v144, 8, v139
	v_fma_f32 v144, v145, s87, 0.5
	v_fma_f32 v145, v151, s87, 0.5
	v_cvt_u32_f32_sdwa v144, v144 dst_sel:WORD_1 dst_unused:UNUSED_PAD src0_sel:DWORD
	v_cvt_u32_f32_sdwa v145, v145 dst_sel:BYTE_3 dst_unused:UNUSED_PAD src0_sel:DWORD
	v_mul_f32_e32 v151, 0xbfb8aa3b, v73
	v_exp_f32_e32 v151, v151
	v_or3_b32 v169, v139, v144, v145
	s_nop 1
	v_permlane16_swap_b32_e32 v166, v167
	v_permlane16_swap_b32_e32 v168, v169
	s_nop 1
	v_permlane32_swap_b32_e32 v166, v168
	v_permlane32_swap_b32_e32 v167, v169
	v_lshl_add_u64 v[170:171], v[142:143], 0, v[172:173]
	global_store_dwordx4 v[170:171], v[166:169], off
	v_mul_f32_e32 v139, 0xbfb8aa3b, v78
	v_mul_f32_e32 v142, 0xbfb8aa3b, v79
	v_exp_f32_e32 v139, v139
	v_exp_f32_e32 v142, v142
	v_mul_f32_e32 v143, 0xbfb8aa3b, v80
	v_mul_f32_e32 v144, 0xbfb8aa3b, v81
	v_add_f32_e32 v139, 1.0, v139
	v_add_f32_e32 v142, 1.0, v142
	v_rcp_f32_e32 v139, v139
	v_rcp_f32_e32 v142, v142
	v_exp_f32_e32 v143, v143
	v_exp_f32_e32 v144, v144
	v_fma_f32 v139, v139, s87, 0.5
	v_fma_f32 v142, v142, s87, 0.5
	v_add_f32_e32 v143, 1.0, v143
	v_add_f32_e32 v144, 1.0, v144
	v_rcp_f32_e32 v143, v143
	v_rcp_f32_e32 v144, v144
	v_cvt_u32_f32_e32 v139, v139
	v_cvt_u32_f32_e32 v142, v142
	v_mul_f32_e32 v145, 0xbfb8aa3b, v72
	v_exp_f32_e32 v145, v145
	v_add_f32_e32 v151, 1.0, v151
	v_lshl_or_b32 v139, v142, 8, v139
	v_fma_f32 v142, v143, s87, 0.5
	v_fma_f32 v143, v144, s87, 0.5
	v_cvt_u32_f32_sdwa v142, v142 dst_sel:WORD_1 dst_unused:UNUSED_PAD src0_sel:DWORD
	v_cvt_u32_f32_sdwa v143, v143 dst_sel:BYTE_3 dst_unused:UNUSED_PAD src0_sel:DWORD
	v_mul_f32_e32 v144, 0xbfb8aa3b, v71
	v_exp_f32_e32 v144, v144
	v_add_f32_e32 v145, 1.0, v145
	v_or3_b32 v166, v139, v142, v143
	v_add_co_u32_e32 v142, vcc, s3, v140
	v_add_f32_e32 v144, 1.0, v144
	s_nop 0
	v_addc_co_u32_e32 v143, vcc, 0, v141, vcc
	v_mul_f32_e32 v139, 0xbfb8aa3b, v70
	v_exp_f32_e32 v139, v139
	v_rcp_f32_e32 v144, v144
	v_rcp_f32_e32 v145, v145
	v_rcp_f32_e32 v151, v151
	v_add_f32_e32 v139, 1.0, v139
	v_rcp_f32_e32 v139, v139
	v_fma_f32 v144, v144, s87, 0.5
	v_cvt_u32_f32_e32 v144, v144
	s_mov_b32 s3, 0x60000
	v_fma_f32 v139, v139, s87, 0.5
	v_cvt_u32_f32_e32 v139, v139
	v_lshl_or_b32 v139, v144, 8, v139
	v_fma_f32 v144, v145, s87, 0.5
	v_fma_f32 v145, v151, s87, 0.5
	v_cvt_u32_f32_sdwa v144, v144 dst_sel:WORD_1 dst_unused:UNUSED_PAD src0_sel:DWORD
	v_cvt_u32_f32_sdwa v145, v145 dst_sel:BYTE_3 dst_unused:UNUSED_PAD src0_sel:DWORD
	v_mul_f32_e32 v151, 0xbfb8aa3b, v77
	v_exp_f32_e32 v151, v151
	v_or3_b32 v167, v139, v144, v145
	v_mul_f32_e32 v139, 0xbfb8aa3b, v74
	v_mul_f32_e32 v144, 0xbfb8aa3b, v75
	v_exp_f32_e32 v139, v139
	v_exp_f32_e32 v144, v144
	v_mul_f32_e32 v145, 0xbfb8aa3b, v76
	v_exp_f32_e32 v145, v145
	v_add_f32_e32 v139, 1.0, v139
	v_add_f32_e32 v144, 1.0, v144
	v_rcp_f32_e32 v139, v139
	v_rcp_f32_e32 v144, v144
	v_add_f32_e32 v145, 1.0, v145
	v_add_f32_e32 v151, 1.0, v151
	v_fma_f32 v139, v139, s87, 0.5
	v_fma_f32 v144, v144, s87, 0.5
	v_rcp_f32_e32 v145, v145
	v_rcp_f32_e32 v151, v151
	v_cvt_u32_f32_e32 v139, v139
	v_cvt_u32_f32_e32 v144, v144
	v_lshl_or_b32 v139, v144, 8, v139
	v_fma_f32 v144, v145, s87, 0.5
	v_fma_f32 v145, v151, s87, 0.5
	v_cvt_u32_f32_sdwa v144, v144 dst_sel:WORD_1 dst_unused:UNUSED_PAD src0_sel:DWORD
	v_cvt_u32_f32_sdwa v145, v145 dst_sel:BYTE_3 dst_unused:UNUSED_PAD src0_sel:DWORD
	v_mul_f32_e32 v151, 0xbfb8aa3b, v69
	v_exp_f32_e32 v151, v151
	v_or3_b32 v168, v139, v144, v145
	v_mul_f32_e32 v139, 0xbfb8aa3b, v66
	v_mul_f32_e32 v144, 0xbfb8aa3b, v67
	v_exp_f32_e32 v139, v139
	v_exp_f32_e32 v144, v144
	v_mul_f32_e32 v145, 0xbfb8aa3b, v68
	v_exp_f32_e32 v145, v145
	v_add_f32_e32 v139, 1.0, v139
	v_add_f32_e32 v144, 1.0, v144
	v_rcp_f32_e32 v139, v139
	v_rcp_f32_e32 v144, v144
	v_add_f32_e32 v145, 1.0, v145
	v_add_f32_e32 v151, 1.0, v151
	v_fma_f32 v139, v139, s87, 0.5
	v_fma_f32 v144, v144, s87, 0.5
	v_rcp_f32_e32 v145, v145
	v_rcp_f32_e32 v151, v151
	v_cvt_u32_f32_e32 v139, v139
	v_cvt_u32_f32_e32 v144, v144
	v_lshl_or_b32 v139, v144, 8, v139
	v_fma_f32 v144, v145, s87, 0.5
	v_fma_f32 v145, v151, s87, 0.5
	v_cvt_u32_f32_sdwa v144, v144 dst_sel:WORD_1 dst_unused:UNUSED_PAD src0_sel:DWORD
	v_cvt_u32_f32_sdwa v145, v145 dst_sel:BYTE_3 dst_unused:UNUSED_PAD src0_sel:DWORD
	v_mul_f32_e32 v151, 0xbfb8aa3b, v57
	v_exp_f32_e32 v151, v151
	v_or3_b32 v169, v139, v144, v145
	s_nop 1
	v_permlane16_swap_b32_e32 v166, v167
;     __device__ __forceinline__ void operator()(const f32x4 (&acc)[2][2][4][2], const pg8::Unit& u, int wr, int wc, int fr_, int fq_) const {
;     ...
; #pragma unroll
;             for (int ai = 0; ai < 2; ++ai)
; #pragma unroll
;                 for (int m = 0; m < 4; ++m) {
;                     unsigned char* rowp = (unsigned char*)G + ((size_t)pm * 256 + ai * 128 + rl0 + m * 16) * 3072 + g0;
; #pragma unroll
;                     for (int bj = 0; bj < 2; ++bj)
; #pragma unroll
;                         for (int n = 0; n < 2; ++n) {
;                             const f32x4 x = acc[ai][bj][m][n]; f32x4 y;
; #pragma unroll
;                             for (int j = 0; j < 4; ++j) y[j] = __builtin_amdgcn_rcpf(1.f + __expf(-x[j]));
;                             const unsigned w = (unsigned)(y[0] * 255.f + 0.5f) | ((unsigned)(y[1] * 255.f + 0.5f) << 8) | ((unsigned)(y[2] * 255.f + 0.5f) << 16) | ((unsigned)(y[3] * 255.f + 0.5f) << 24);
;                             *(unsigned*)(rowp + 128 * bj + 16 * n) = w;
	v_permlane16_swap_b32_e32 v168, v169
	s_nop 1
	v_permlane32_swap_b32_e32 v166, v168
	v_permlane32_swap_b32_e32 v167, v169
	v_lshl_add_u64 v[170:171], v[142:143], 0, v[172:173]
	global_store_dwordx4 v[170:171], v[166:169], off
	v_mul_f32_e32 v139, 0xbfb8aa3b, v62
	v_mul_f32_e32 v142, 0xbfb8aa3b, v63
	v_exp_f32_e32 v139, v139
	v_exp_f32_e32 v142, v142
	v_mul_f32_e32 v143, 0xbfb8aa3b, v64
	v_mul_f32_e32 v144, 0xbfb8aa3b, v65
	v_add_f32_e32 v139, 1.0, v139
	v_add_f32_e32 v142, 1.0, v142
	v_rcp_f32_e32 v139, v139
	v_rcp_f32_e32 v142, v142
	v_exp_f32_e32 v143, v143
	v_exp_f32_e32 v144, v144
	v_fma_f32 v139, v139, s87, 0.5
	v_fma_f32 v142, v142, s87, 0.5
	v_add_f32_e32 v143, 1.0, v143
	v_add_f32_e32 v144, 1.0, v144
	v_rcp_f32_e32 v143, v143
	v_rcp_f32_e32 v144, v144
	v_cvt_u32_f32_e32 v139, v139
	v_cvt_u32_f32_e32 v142, v142
	v_mul_f32_e32 v145, 0xbfb8aa3b, v56
	v_exp_f32_e32 v145, v145
	v_add_f32_e32 v151, 1.0, v151
	v_lshl_or_b32 v139, v142, 8, v139
	v_fma_f32 v142, v143, s87, 0.5
	v_fma_f32 v143, v144, s87, 0.5
	v_cvt_u32_f32_sdwa v142, v142 dst_sel:WORD_1 dst_unused:UNUSED_PAD src0_sel:DWORD
	v_cvt_u32_f32_sdwa v143, v143 dst_sel:BYTE_3 dst_unused:UNUSED_PAD src0_sel:DWORD
	v_mul_f32_e32 v144, 0xbfb8aa3b, v55
	v_exp_f32_e32 v144, v144
	v_add_f32_e32 v145, 1.0, v145
	v_or3_b32 v166, v139, v142, v143
	v_add_co_u32_e32 v142, vcc, s3, v140
	v_add_f32_e32 v144, 1.0, v144
	s_nop 0
	v_addc_co_u32_e32 v143, vcc, 0, v141, vcc
	v_mul_f32_e32 v139, 0xbfb8aa3b, v54
	v_exp_f32_e32 v139, v139
	v_rcp_f32_e32 v144, v144
	v_rcp_f32_e32 v145, v145
	v_rcp_f32_e32 v151, v151
	v_add_f32_e32 v139, 1.0, v139
	v_rcp_f32_e32 v139, v139
	v_fma_f32 v144, v144, s87, 0.5
	v_cvt_u32_f32_e32 v144, v144
	s_mov_b32 s3, 0x6c000
	v_fma_f32 v139, v139, s87, 0.5
	v_cvt_u32_f32_e32 v139, v139
	v_lshl_or_b32 v139, v144, 8, v139
	v_fma_f32 v144, v145, s87, 0.5
	v_fma_f32 v145, v151, s87, 0.5
	v_cvt_u32_f32_sdwa v144, v144 dst_sel:WORD_1 dst_unused:UNUSED_PAD src0_sel:DWORD
	v_cvt_u32_f32_sdwa v145, v145 dst_sel:BYTE_3 dst_unused:UNUSED_PAD src0_sel:DWORD
	v_mul_f32_e32 v151, 0xbfb8aa3b, v61
	v_exp_f32_e32 v151, v151
	v_or3_b32 v167, v139, v144, v145
	v_mul_f32_e32 v139, 0xbfb8aa3b, v58
	v_mul_f32_e32 v144, 0xbfb8aa3b, v59
	v_exp_f32_e32 v139, v139
	v_exp_f32_e32 v144, v144
	v_mul_f32_e32 v145, 0xbfb8aa3b, v60
	v_exp_f32_e32 v145, v145
	v_add_f32_e32 v139, 1.0, v139
	v_add_f32_e32 v144, 1.0, v144
	v_rcp_f32_e32 v139, v139
	v_rcp_f32_e32 v144, v144
	v_add_f32_e32 v145, 1.0, v145
	v_add_f32_e32 v151, 1.0, v151
	v_fma_f32 v139, v139, s87, 0.5
	v_fma_f32 v144, v144, s87, 0.5
	v_rcp_f32_e32 v145, v145
	v_rcp_f32_e32 v151, v151
	v_cvt_u32_f32_e32 v139, v139
	v_cvt_u32_f32_e32 v144, v144
	v_lshl_or_b32 v139, v144, 8, v139
	v_fma_f32 v144, v145, s87, 0.5
	v_fma_f32 v145, v151, s87, 0.5
	v_cvt_u32_f32_sdwa v144, v144 dst_sel:WORD_1 dst_unused:UNUSED_PAD src0_sel:DWORD
	v_cvt_u32_f32_sdwa v145, v145 dst_sel:BYTE_3 dst_unused:UNUSED_PAD src0_sel:DWORD
	v_mul_f32_e32 v151, 0xbfb8aa3b, v53
	v_exp_f32_e32 v151, v151
	v_or3_b32 v168, v139, v144, v145
	v_mul_f32_e32 v139, 0xbfb8aa3b, v50
	v_mul_f32_e32 v144, 0xbfb8aa3b, v51
	v_exp_f32_e32 v139, v139
	v_exp_f32_e32 v144, v144
	v_mul_f32_e32 v145, 0xbfb8aa3b, v52
	v_exp_f32_e32 v145, v145
	v_add_f32_e32 v139, 1.0, v139
	v_add_f32_e32 v144, 1.0, v144
	v_rcp_f32_e32 v139, v139
	v_rcp_f32_e32 v144, v144
	v_add_f32_e32 v145, 1.0, v145
	v_add_f32_e32 v151, 1.0, v151
	v_fma_f32 v139, v139, s87, 0.5
	v_fma_f32 v144, v144, s87, 0.5
	v_rcp_f32_e32 v145, v145
	v_rcp_f32_e32 v151, v151
	v_cvt_u32_f32_e32 v139, v139
	v_cvt_u32_f32_e32 v144, v144
	v_lshl_or_b32 v139, v144, 8, v139
	v_fma_f32 v144, v145, s87, 0.5
	v_fma_f32 v145, v151, s87, 0.5
	v_cvt_u32_f32_sdwa v144, v144 dst_sel:WORD_1 dst_unused:UNUSED_PAD src0_sel:DWORD
	v_cvt_u32_f32_sdwa v145, v145 dst_sel:BYTE_3 dst_unused:UNUSED_PAD src0_sel:DWORD
	v_mul_f32_e32 v151, 0xbfb8aa3b, v41
	v_exp_f32_e32 v151, v151
	v_or3_b32 v169, v139, v144, v145
	s_nop 1
	v_permlane16_swap_b32_e32 v166, v167
	v_permlane16_swap_b32_e32 v168, v169
	s_nop 1
	v_permlane32_swap_b32_e32 v166, v168
	v_permlane32_swap_b32_e32 v167, v169
	v_lshl_add_u64 v[170:171], v[142:143], 0, v[172:173]
	global_store_dwordx4 v[170:171], v[166:169], off
	v_mul_f32_e32 v139, 0xbfb8aa3b, v46
	v_mul_f32_e32 v142, 0xbfb8aa3b, v47
	v_exp_f32_e32 v139, v139
	v_exp_f32_e32 v142, v142
	v_mul_f32_e32 v143, 0xbfb8aa3b, v48
	v_mul_f32_e32 v144, 0xbfb8aa3b, v49
	v_add_f32_e32 v139, 1.0, v139
	v_add_f32_e32 v142, 1.0, v142
	v_rcp_f32_e32 v139, v139
	v_rcp_f32_e32 v142, v142
	v_exp_f32_e32 v143, v143
	v_exp_f32_e32 v144, v144
	v_fma_f32 v139, v139, s87, 0.5
	v_fma_f32 v142, v142, s87, 0.5
	v_add_f32_e32 v143, 1.0, v143
	v_add_f32_e32 v144, 1.0, v144
	v_rcp_f32_e32 v143, v143
	v_rcp_f32_e32 v144, v144
	v_cvt_u32_f32_e32 v139, v139
	v_cvt_u32_f32_e32 v142, v142
	v_mul_f32_e32 v145, 0xbfb8aa3b, v40
	v_exp_f32_e32 v145, v145
	v_add_f32_e32 v151, 1.0, v151
	v_lshl_or_b32 v139, v142, 8, v139
	v_fma_f32 v142, v143, s87, 0.5
	v_fma_f32 v143, v144, s87, 0.5
	v_cvt_u32_f32_sdwa v142, v142 dst_sel:WORD_1 dst_unused:UNUSED_PAD src0_sel:DWORD
	v_cvt_u32_f32_sdwa v143, v143 dst_sel:BYTE_3 dst_unused:UNUSED_PAD src0_sel:DWORD
	v_mul_f32_e32 v144, 0xbfb8aa3b, v39
	v_exp_f32_e32 v144, v144
	v_add_f32_e32 v145, 1.0, v145
	v_or3_b32 v166, v139, v142, v143
	v_add_co_u32_e32 v142, vcc, s3, v140
	v_add_f32_e32 v144, 1.0, v144
	s_nop 0
	v_addc_co_u32_e32 v143, vcc, 0, v141, vcc
	v_mul_f32_e32 v139, 0xbfb8aa3b, v38
	v_exp_f32_e32 v139, v139
	v_rcp_f32_e32 v144, v144
	v_rcp_f32_e32 v145, v145
	v_rcp_f32_e32 v151, v151
	v_add_f32_e32 v139, 1.0, v139
	v_rcp_f32_e32 v139, v139
;     __device__ __forceinline__ void operator()(const f32x4 (&acc)[2][2][4][2], const pg8::Unit& u, int wr, int wc, int fr_, int fq_) const {
;     ...
; #pragma unroll
;             for (int ai = 0; ai < 2; ++ai)
; #pragma unroll
;                 for (int m = 0; m < 4; ++m) {
;                     unsigned char* rowp = (unsigned char*)G + ((size_t)pm * 256 + ai * 128 + rl0 + m * 16) * 3072 + g0;
; #pragma unroll
;                     for (int bj = 0; bj < 2; ++bj)
; #pragma unroll
;                         for (int n = 0; n < 2; ++n) {
;                             const f32x4 x = acc[ai][bj][m][n]; f32x4 y;
; #pragma unroll
;                             for (int j = 0; j < 4; ++j) y[j] = __builtin_amdgcn_rcpf(1.f + __expf(-x[j]));
;                             const unsigned w = (unsigned)(y[0] * 255.f + 0.5f) | ((unsigned)(y[1] * 255.f + 0.5f) << 8) | ((unsigned)(y[2] * 255.f + 0.5f) << 16) | ((unsigned)(y[3] * 255.f + 0.5f) << 24);
;                             *(unsigned*)(rowp + 128 * bj + 16 * n) = w;
	v_fma_f32 v144, v144, s87, 0.5
	v_cvt_u32_f32_e32 v144, v144
	s_mov_b32 s3, 0x78000
	v_fma_f32 v139, v139, s87, 0.5
	v_cvt_u32_f32_e32 v139, v139
	v_lshl_or_b32 v139, v144, 8, v139
	v_fma_f32 v144, v145, s87, 0.5
	v_fma_f32 v145, v151, s87, 0.5
	v_cvt_u32_f32_sdwa v144, v144 dst_sel:WORD_1 dst_unused:UNUSED_PAD src0_sel:DWORD
	v_cvt_u32_f32_sdwa v145, v145 dst_sel:BYTE_3 dst_unused:UNUSED_PAD src0_sel:DWORD
	v_mul_f32_e32 v151, 0xbfb8aa3b, v45
	v_exp_f32_e32 v151, v151
	v_or3_b32 v167, v139, v144, v145
	v_mul_f32_e32 v139, 0xbfb8aa3b, v42
	v_mul_f32_e32 v144, 0xbfb8aa3b, v43
	v_exp_f32_e32 v139, v139
	v_exp_f32_e32 v144, v144
	v_mul_f32_e32 v145, 0xbfb8aa3b, v44
	v_exp_f32_e32 v145, v145
	v_add_f32_e32 v139, 1.0, v139
	v_add_f32_e32 v144, 1.0, v144
	v_rcp_f32_e32 v139, v139
	v_rcp_f32_e32 v144, v144
	v_add_f32_e32 v145, 1.0, v145
	v_add_f32_e32 v151, 1.0, v151
	v_fma_f32 v139, v139, s87, 0.5
	v_fma_f32 v144, v144, s87, 0.5
	v_rcp_f32_e32 v145, v145
	v_rcp_f32_e32 v151, v151
	v_cvt_u32_f32_e32 v139, v139
	v_cvt_u32_f32_e32 v144, v144
	v_lshl_or_b32 v139, v144, 8, v139
	v_fma_f32 v144, v145, s87, 0.5
	v_fma_f32 v145, v151, s87, 0.5
	v_cvt_u32_f32_sdwa v144, v144 dst_sel:WORD_1 dst_unused:UNUSED_PAD src0_sel:DWORD
	v_cvt_u32_f32_sdwa v145, v145 dst_sel:BYTE_3 dst_unused:UNUSED_PAD src0_sel:DWORD
	v_mul_f32_e32 v151, 0xbfb8aa3b, v37
	v_exp_f32_e32 v151, v151
	v_or3_b32 v168, v139, v144, v145
	v_mul_f32_e32 v139, 0xbfb8aa3b, v34
	v_mul_f32_e32 v144, 0xbfb8aa3b, v35
	v_exp_f32_e32 v139, v139
	v_exp_f32_e32 v144, v144
	v_mul_f32_e32 v145, 0xbfb8aa3b, v36
	v_exp_f32_e32 v145, v145
	v_add_f32_e32 v139, 1.0, v139
	v_add_f32_e32 v144, 1.0, v144
	v_rcp_f32_e32 v139, v139
	v_rcp_f32_e32 v144, v144
	v_add_f32_e32 v145, 1.0, v145
	v_add_f32_e32 v151, 1.0, v151
	v_fma_f32 v139, v139, s87, 0.5
	v_fma_f32 v144, v144, s87, 0.5
	v_rcp_f32_e32 v145, v145
	v_rcp_f32_e32 v151, v151
	v_cvt_u32_f32_e32 v139, v139
	v_cvt_u32_f32_e32 v144, v144
	v_lshl_or_b32 v139, v144, 8, v139
	v_fma_f32 v144, v145, s87, 0.5
	v_fma_f32 v145, v151, s87, 0.5
	v_cvt_u32_f32_sdwa v144, v144 dst_sel:WORD_1 dst_unused:UNUSED_PAD src0_sel:DWORD
	v_cvt_u32_f32_sdwa v145, v145 dst_sel:BYTE_3 dst_unused:UNUSED_PAD src0_sel:DWORD
	v_mul_f32_e32 v151, 0xbfb8aa3b, v25
	v_exp_f32_e32 v151, v151
	v_or3_b32 v169, v139, v144, v145
	s_nop 1
	v_permlane16_swap_b32_e32 v166, v167
	v_permlane16_swap_b32_e32 v168, v169
	s_nop 1
	v_permlane32_swap_b32_e32 v166, v168
	v_permlane32_swap_b32_e32 v167, v169
	v_lshl_add_u64 v[170:171], v[142:143], 0, v[172:173]
	global_store_dwordx4 v[170:171], v[166:169], off
	v_mul_f32_e32 v139, 0xbfb8aa3b, v30
	v_mul_f32_e32 v142, 0xbfb8aa3b, v31
	v_exp_f32_e32 v139, v139
	v_exp_f32_e32 v142, v142
	v_mul_f32_e32 v143, 0xbfb8aa3b, v32
	v_mul_f32_e32 v144, 0xbfb8aa3b, v33
	v_add_f32_e32 v139, 1.0, v139
	v_add_f32_e32 v142, 1.0, v142
	v_rcp_f32_e32 v139, v139
	v_rcp_f32_e32 v142, v142
	v_exp_f32_e32 v143, v143
	v_exp_f32_e32 v144, v144
	v_fma_f32 v139, v139, s87, 0.5
	v_fma_f32 v142, v142, s87, 0.5
	v_add_f32_e32 v143, 1.0, v143
	v_add_f32_e32 v144, 1.0, v144
	v_rcp_f32_e32 v143, v143
	v_rcp_f32_e32 v144, v144
	v_cvt_u32_f32_e32 v139, v139
	v_cvt_u32_f32_e32 v142, v142
	v_mul_f32_e32 v145, 0xbfb8aa3b, v24
	v_exp_f32_e32 v145, v145
	v_add_f32_e32 v151, 1.0, v151
	v_lshl_or_b32 v139, v142, 8, v139
	v_fma_f32 v142, v143, s87, 0.5
	v_fma_f32 v143, v144, s87, 0.5
	v_cvt_u32_f32_sdwa v142, v142 dst_sel:WORD_1 dst_unused:UNUSED_PAD src0_sel:DWORD
	v_cvt_u32_f32_sdwa v143, v143 dst_sel:BYTE_3 dst_unused:UNUSED_PAD src0_sel:DWORD
	v_mul_f32_e32 v144, 0xbfb8aa3b, v23
	v_exp_f32_e32 v144, v144
	v_add_f32_e32 v145, 1.0, v145
	v_or3_b32 v166, v139, v142, v143
	v_add_co_u32_e32 v142, vcc, s3, v140
	v_add_f32_e32 v144, 1.0, v144
	s_nop 0
	v_addc_co_u32_e32 v143, vcc, 0, v141, vcc
	v_mul_f32_e32 v139, 0xbfb8aa3b, v22
	v_exp_f32_e32 v139, v139
	v_rcp_f32_e32 v144, v144
	v_rcp_f32_e32 v145, v145
	v_rcp_f32_e32 v151, v151
	v_add_f32_e32 v139, 1.0, v139
	v_rcp_f32_e32 v139, v139
	v_fma_f32 v144, v144, s87, 0.5
	v_cvt_u32_f32_e32 v144, v144
	s_mov_b32 s3, 0x84000
	v_fma_f32 v139, v139, s87, 0.5
	v_cvt_u32_f32_e32 v139, v139
	v_add_co_u32_e32 v140, vcc, s3, v140
	v_lshl_or_b32 v139, v144, 8, v139
	v_fma_f32 v144, v145, s87, 0.5
	v_fma_f32 v145, v151, s87, 0.5
	v_cvt_u32_f32_sdwa v144, v144 dst_sel:WORD_1 dst_unused:UNUSED_PAD src0_sel:DWORD
	v_cvt_u32_f32_sdwa v145, v145 dst_sel:BYTE_3 dst_unused:UNUSED_PAD src0_sel:DWORD
	v_mul_f32_e32 v151, 0xbfb8aa3b, v29
	v_exp_f32_e32 v151, v151
	v_addc_co_u32_e32 v141, vcc, 0, v141, vcc
	v_or3_b32 v167, v139, v144, v145
	v_mul_f32_e32 v139, 0xbfb8aa3b, v26
	v_mul_f32_e32 v144, 0xbfb8aa3b, v27
	v_exp_f32_e32 v139, v139
	v_exp_f32_e32 v144, v144
	v_mul_f32_e32 v145, 0xbfb8aa3b, v28
	v_exp_f32_e32 v145, v145
	v_add_f32_e32 v139, 1.0, v139
	v_add_f32_e32 v144, 1.0, v144
	v_rcp_f32_e32 v139, v139
	v_rcp_f32_e32 v144, v144
	v_add_f32_e32 v145, 1.0, v145
	v_add_f32_e32 v151, 1.0, v151
	v_fma_f32 v139, v139, s87, 0.5
	v_fma_f32 v144, v144, s87, 0.5
	v_rcp_f32_e32 v145, v145
	v_rcp_f32_e32 v151, v151
	v_cvt_u32_f32_e32 v139, v139
	v_cvt_u32_f32_e32 v144, v144
	v_lshl_or_b32 v139, v144, 8, v139
	v_fma_f32 v144, v145, s87, 0.5
	v_fma_f32 v145, v151, s87, 0.5
;     __device__ __forceinline__ void operator()(const f32x4 (&acc)[2][2][4][2], const pg8::Unit& u, int wr, int wc, int fr_, int fq_) const {
;     ...
; #pragma unroll
;             for (int ai = 0; ai < 2; ++ai)
; #pragma unroll
;                 for (int m = 0; m < 4; ++m) {
;                     unsigned char* rowp = (unsigned char*)G + ((size_t)pm * 256 + ai * 128 + rl0 + m * 16) * 3072 + g0;
; #pragma unroll
;                     for (int bj = 0; bj < 2; ++bj)
; #pragma unroll
;                         for (int n = 0; n < 2; ++n) {
;                             const f32x4 x = acc[ai][bj][m][n]; f32x4 y;
; #pragma unroll
;                             for (int j = 0; j < 4; ++j) y[j] = __builtin_amdgcn_rcpf(1.f + __expf(-x[j]));
;                             const unsigned w = (unsigned)(y[0] * 255.f + 0.5f) | ((unsigned)(y[1] * 255.f + 0.5f) << 8) | ((unsigned)(y[2] * 255.f + 0.5f) << 16) | ((unsigned)(y[3] * 255.f + 0.5f) << 24);
;                             *(unsigned*)(rowp + 128 * bj + 16 * n) = w;
	v_cvt_u32_f32_sdwa v144, v144 dst_sel:WORD_1 dst_unused:UNUSED_PAD src0_sel:DWORD
	v_cvt_u32_f32_sdwa v145, v145 dst_sel:BYTE_3 dst_unused:UNUSED_PAD src0_sel:DWORD
	v_mul_f32_e32 v151, 0xbfb8aa3b, v21
	v_exp_f32_e32 v151, v151
	v_or3_b32 v168, v139, v144, v145
	v_mul_f32_e32 v139, 0xbfb8aa3b, v18
	v_mul_f32_e32 v144, 0xbfb8aa3b, v19
	v_exp_f32_e32 v139, v139
	v_exp_f32_e32 v144, v144
	v_mul_f32_e32 v145, 0xbfb8aa3b, v20
	v_exp_f32_e32 v145, v145
	v_add_f32_e32 v139, 1.0, v139
	v_add_f32_e32 v144, 1.0, v144
	v_rcp_f32_e32 v139, v139
	v_rcp_f32_e32 v144, v144
	v_add_f32_e32 v145, 1.0, v145
	v_add_f32_e32 v151, 1.0, v151
	v_fma_f32 v139, v139, s87, 0.5
	v_fma_f32 v144, v144, s87, 0.5
	v_rcp_f32_e32 v145, v145
	v_rcp_f32_e32 v151, v151
	v_cvt_u32_f32_e32 v139, v139
	v_cvt_u32_f32_e32 v144, v144
	v_lshl_or_b32 v139, v144, 8, v139
	v_fma_f32 v144, v145, s87, 0.5
	v_fma_f32 v145, v151, s87, 0.5
	v_cvt_u32_f32_sdwa v144, v144 dst_sel:WORD_1 dst_unused:UNUSED_PAD src0_sel:DWORD
	v_cvt_u32_f32_sdwa v145, v145 dst_sel:BYTE_3 dst_unused:UNUSED_PAD src0_sel:DWORD
	s_nop 0
	v_or3_b32 v169, v139, v144, v145
	s_nop 1
	v_permlane16_swap_b32_e32 v166, v167
	v_permlane16_swap_b32_e32 v168, v169
	s_nop 1
	v_permlane32_swap_b32_e32 v166, v168
	v_permlane32_swap_b32_e32 v167, v169
	v_lshl_add_u64 v[170:171], v[142:143], 0, v[172:173]
	global_store_dwordx4 v[170:171], v[166:169], off
	v_mul_f32_e32 v139, 0xbfb8aa3b, v14
	v_mul_f32_e32 v142, 0xbfb8aa3b, v15
	v_exp_f32_e32 v139, v139
	v_exp_f32_e32 v142, v142
	v_mul_f32_e32 v143, 0xbfb8aa3b, v16
	v_mul_f32_e32 v144, 0xbfb8aa3b, v17
	v_add_f32_e32 v139, 1.0, v139
	v_add_f32_e32 v142, 1.0, v142
	v_rcp_f32_e32 v139, v139
	v_rcp_f32_e32 v142, v142
	v_exp_f32_e32 v143, v143
	v_exp_f32_e32 v144, v144
	v_fma_f32 v139, v139, s87, 0.5
	v_fma_f32 v142, v142, s87, 0.5
	v_add_f32_e32 v143, 1.0, v143
	v_add_f32_e32 v144, 1.0, v144
	v_rcp_f32_e32 v143, v143
	v_rcp_f32_e32 v144, v144
	v_cvt_u32_f32_e32 v139, v139
	v_cvt_u32_f32_e32 v142, v142
	v_lshl_or_b32 v139, v142, 8, v139
	v_fma_f32 v142, v143, s87, 0.5
	v_fma_f32 v143, v144, s87, 0.5
	v_cvt_u32_f32_sdwa v142, v142 dst_sel:WORD_1 dst_unused:UNUSED_PAD src0_sel:DWORD
	v_cvt_u32_f32_sdwa v143, v143 dst_sel:BYTE_3 dst_unused:UNUSED_PAD src0_sel:DWORD
	v_mul_f32_e32 v144, 0xbfb8aa3b, v9
	v_exp_f32_e32 v144, v144
	v_or3_b32 v166, v139, v142, v143
	v_mul_f32_e32 v139, 0xbfb8aa3b, v6
	v_mul_f32_e32 v142, 0xbfb8aa3b, v7
	v_exp_f32_e32 v139, v139
	v_exp_f32_e32 v142, v142
	v_mul_f32_e32 v143, 0xbfb8aa3b, v8
	v_exp_f32_e32 v143, v143
	v_add_f32_e32 v139, 1.0, v139
	v_add_f32_e32 v142, 1.0, v142
	v_rcp_f32_e32 v139, v139
	v_rcp_f32_e32 v142, v142
	v_add_f32_e32 v143, 1.0, v143
	v_add_f32_e32 v144, 1.0, v144
	v_fma_f32 v139, v139, s87, 0.5
	v_fma_f32 v142, v142, s87, 0.5
	v_rcp_f32_e32 v143, v143
	v_rcp_f32_e32 v144, v144
	v_cvt_u32_f32_e32 v139, v139
	v_cvt_u32_f32_e32 v142, v142
	v_lshl_or_b32 v139, v142, 8, v139
	v_fma_f32 v142, v143, s87, 0.5
	v_fma_f32 v143, v144, s87, 0.5
	v_cvt_u32_f32_sdwa v142, v142 dst_sel:WORD_1 dst_unused:UNUSED_PAD src0_sel:DWORD
	v_cvt_u32_f32_sdwa v143, v143 dst_sel:BYTE_3 dst_unused:UNUSED_PAD src0_sel:DWORD
	v_mul_f32_e32 v144, 0xbfb8aa3b, v13
	v_exp_f32_e32 v144, v144
	v_or3_b32 v167, v139, v142, v143
	v_mul_f32_e32 v139, 0xbfb8aa3b, v10
	v_mul_f32_e32 v142, 0xbfb8aa3b, v11
	v_exp_f32_e32 v139, v139
	v_exp_f32_e32 v142, v142
	v_mul_f32_e32 v143, 0xbfb8aa3b, v12
	v_exp_f32_e32 v143, v143
	v_add_f32_e32 v139, 1.0, v139
	v_add_f32_e32 v142, 1.0, v142
	v_rcp_f32_e32 v139, v139
	v_rcp_f32_e32 v142, v142
	v_add_f32_e32 v143, 1.0, v143
	v_add_f32_e32 v144, 1.0, v144
	v_fma_f32 v139, v139, s87, 0.5
	v_fma_f32 v142, v142, s87, 0.5
	v_rcp_f32_e32 v143, v143
	v_rcp_f32_e32 v144, v144
	v_cvt_u32_f32_e32 v139, v139
	v_cvt_u32_f32_e32 v142, v142
	v_lshl_or_b32 v139, v142, 8, v139
	v_fma_f32 v142, v143, s87, 0.5
	v_fma_f32 v143, v144, s87, 0.5
	v_cvt_u32_f32_sdwa v142, v142 dst_sel:WORD_1 dst_unused:UNUSED_PAD src0_sel:DWORD
	v_cvt_u32_f32_sdwa v143, v143 dst_sel:BYTE_3 dst_unused:UNUSED_PAD src0_sel:DWORD
	v_mul_f32_e32 v144, 0xbfb8aa3b, v5
	v_exp_f32_e32 v144, v144
	v_or3_b32 v168, v139, v142, v143
	v_mul_f32_e32 v139, 0xbfb8aa3b, v2
	v_mul_f32_e32 v142, 0xbfb8aa3b, v3
	v_exp_f32_e32 v139, v139
	v_exp_f32_e32 v142, v142
	v_mul_f32_e32 v143, 0xbfb8aa3b, v4
	v_exp_f32_e32 v143, v143
	v_add_f32_e32 v139, 1.0, v139
	v_add_f32_e32 v142, 1.0, v142
	v_rcp_f32_e32 v139, v139
	v_rcp_f32_e32 v142, v142
	v_add_f32_e32 v143, 1.0, v143
	v_add_f32_e32 v144, 1.0, v144
	v_fma_f32 v139, v139, s87, 0.5
	v_fma_f32 v142, v142, s87, 0.5
	v_rcp_f32_e32 v143, v143
	v_rcp_f32_e32 v144, v144
	v_cvt_u32_f32_e32 v139, v139
	v_cvt_u32_f32_e32 v142, v142
	v_lshl_or_b32 v139, v142, 8, v139
	v_fma_f32 v142, v143, s87, 0.5
	v_fma_f32 v143, v144, s87, 0.5
	v_cvt_u32_f32_sdwa v142, v142 dst_sel:WORD_1 dst_unused:UNUSED_PAD src0_sel:DWORD
	v_cvt_u32_f32_sdwa v143, v143 dst_sel:BYTE_3 dst_unused:UNUSED_PAD src0_sel:DWORD
	s_nop 0
	v_or3_b32 v169, v139, v142, v143
	s_nop 1
	v_permlane16_swap_b32_e32 v166, v167
	v_permlane16_swap_b32_e32 v168, v169
	s_nop 1
	v_permlane32_swap_b32_e32 v166, v168
	v_permlane32_swap_b32_e32 v167, v169
	v_lshl_add_u64 v[170:171], v[140:141], 0, v[172:173]
	global_store_dwordx4 v[170:171], v[166:169], off
